# ML_SCAN: 37 v_max(x,x) canonicalisations removed from the per-chunk running-max chain (readers take x directly)
# baseline (speedup 1.0000x reference)
; __device__ __forceinline__ float ex2(float x) { return __builtin_amdgcn_exp2f(x); }
; __device__ __forceinline__ void ml_scan_phase(float* KV, const float* MLOC, const float* BLAST, float* MPREV) {
;     ...
;         for (int j = 0; j < 16; ++j) { p0[(size_t)(k0 + j) * ML_KVSZ] = C0; if (el0 == 0) MPREV[bh0 * 128 + k0 + j] = m0;
;             const float M = fmaxf(m0, ml0[j]); C0 = ex2(m0 - M) * C0 + ex2(ml0[j] - M) * v0[j]; m0 = bl0[j] + M; }
;         if (e1 >= 0) {
; #pragma unroll
;             for (int j = 0; j < 16; ++j) { p1[(size_t)(k0 + j) * ML_KVSZ] = C1; if (el1 == 0) MPREV[bh1 * 128 + k0 + j] = m1;
;                 const float M = fmaxf(m1, ml1[j]); C1 = ex2(m1 - M) * C1 + ex2(ml1[j] - M) * v1[j]; m1 = bl1[j] + M; } }
.LBB0_249:
	s_or_b64 exec, exec, s[8:9]
	s_waitcnt vmcnt(23)
	v_max_f32_e32 v122, v74, v74
	v_max_f32_e32 v121, v105, v122
	v_sub_f32_e32 v74, v74, v121
	v_sub_f32_e32 v105, v105, v121
	v_exp_f32_e32 v74, v74
	v_exp_f32_e32 v105, v105
	s_mov_b64 s[4:5], 0x13568100
	v_lshl_add_u64 v[122:123], v[102:103], 0, s[4:5]
	v_mul_f32_e32 v74, v119, v74
	v_fmac_f32_e32 v74, v104, v105
	s_waitcnt vmcnt(19)
	v_add_f32_e32 v84, v84, v121
	global_store_dword v[122:123], v74, off
	s_and_saveexec_b64 s[8:9], s[42:43]
	s_cbranch_execz .LBB0_251
	v_add_co_u32_e32 v104, vcc, 0x175e4000, v100
	s_nop 1
	v_addc_co_u32_e32 v105, vcc, 0, v101, vcc
	global_store_dword v[104:105], v84, off offset:4

; __device__ __forceinline__ float ex2(float x) { return __builtin_amdgcn_exp2f(x); }
; __device__ __forceinline__ void ml_scan_phase(float* KV, const float* MLOC, const float* BLAST, float* MPREV) {
;     ...
;         for (int j = 0; j < 16; ++j) { p0[(size_t)(k0 + j) * ML_KVSZ] = C0; if (el0 == 0) MPREV[bh0 * 128 + k0 + j] = m0;
;             const float M = fmaxf(m0, ml0[j]); C0 = ex2(m0 - M) * C0 + ex2(ml0[j] - M) * v0[j]; m0 = bl0[j] + M; }
;         if (e1 >= 0) {
; #pragma unroll
;             for (int j = 0; j < 16; ++j) { p1[(size_t)(k0 + j) * ML_KVSZ] = C1; if (el1 == 0) MPREV[bh1 * 128 + k0 + j] = m1;
;                 const float M = fmaxf(m1, ml1[j]); C1 = ex2(m1 - M) * C1 + ex2(ml1[j] - M) * v1[j]; m1 = bl1[j] + M; } }
.LBB0_255:
	s_or_b64 exec, exec, s[8:9]
	v_max_f32_e32 v84, v75, v77
	v_sub_f32_e32 v76, v77, v84
	v_sub_f32_e32 v75, v75, v84
	v_exp_f32_e32 v85, v76
	v_exp_f32_e32 v86, v75
	s_mov_b64 s[4:5], 0x13580400
	v_lshl_add_u64 v[76:77], v[102:103], 0, s[4:5]
	s_waitcnt vmcnt(16)
	v_mul_f32_e32 v75, v117, v85
	v_fmac_f32_e32 v75, v74, v86
	v_add_f32_e32 v74, v87, v84
	global_store_dword v[76:77], v75, off
	s_and_saveexec_b64 s[8:9], s[42:43]
	s_cbranch_execz .LBB0_257
	v_add_co_u32_e32 v76, vcc, 0x175e4000, v100
	s_nop 1
	v_addc_co_u32_e32 v77, vcc, 0, v101, vcc
	global_store_dword v[76:77], v74, off offset:16

; __device__ __forceinline__ float ex2(float x) { return __builtin_amdgcn_exp2f(x); }
; __device__ __forceinline__ void ml_scan_phase(float* KV, const float* MLOC, const float* BLAST, float* MPREV) {
;     ...
;         for (int j = 0; j < 16; ++j) { p0[(size_t)(k0 + j) * ML_KVSZ] = C0; if (el0 == 0) MPREV[bh0 * 128 + k0 + j] = m0;
;             const float M = fmaxf(m0, ml0[j]); C0 = ex2(m0 - M) * C0 + ex2(ml0[j] - M) * v0[j]; m0 = bl0[j] + M; }
;         if (e1 >= 0) {
; #pragma unroll
;             for (int j = 0; j < 16; ++j) { p1[(size_t)(k0 + j) * ML_KVSZ] = C1; if (el1 == 0) MPREV[bh1 * 128 + k0 + j] = m1;
;                 const float M = fmaxf(m1, ml1[j]); C1 = ex2(m1 - M) * C1 + ex2(ml1[j] - M) * v1[j]; m1 = bl1[j] + M; } }
.LBB0_263:
	s_or_b64 exec, exec, s[8:9]
	v_max_f32_e32 v70, v67, v69
	v_sub_f32_e32 v68, v69, v70
	v_sub_f32_e32 v67, v67, v70
	v_exp_f32_e32 v71, v68
	v_exp_f32_e32 v72, v67
	s_mov_b64 s[4:5], 0x135a0800
	v_lshl_add_u64 v[68:69], v[102:103], 0, s[4:5]
	s_waitcnt vmcnt(16)
	v_mul_f32_e32 v67, v113, v71
	v_fmac_f32_e32 v67, v66, v72
	v_add_f32_e32 v66, v73, v70
	global_store_dword v[68:69], v67, off
	s_and_saveexec_b64 s[8:9], s[42:43]
	s_cbranch_execz .LBB0_265
	v_add_co_u32_e32 v68, vcc, 0x175e4000, v100
	s_nop 1
	v_addc_co_u32_e32 v69, vcc, 0, v101, vcc
	global_store_dword v[68:69], v66, off offset:32

; __device__ __forceinline__ float ex2(float x) { return __builtin_amdgcn_exp2f(x); }
; __device__ __forceinline__ void ml_scan_phase(float* KV, const float* MLOC, const float* BLAST, float* MPREV) {
;     ...
;         for (int j = 0; j < 16; ++j) { p0[(size_t)(k0 + j) * ML_KVSZ] = C0; if (el0 == 0) MPREV[bh0 * 128 + k0 + j] = m0;
;             const float M = fmaxf(m0, ml0[j]); C0 = ex2(m0 - M) * C0 + ex2(ml0[j] - M) * v0[j]; m0 = bl0[j] + M; }
;         if (e1 >= 0) {
; #pragma unroll
;             for (int j = 0; j < 16; ++j) { p1[(size_t)(k0 + j) * ML_KVSZ] = C1; if (el1 == 0) MPREV[bh1 * 128 + k0 + j] = m1;
;                 const float M = fmaxf(m1, ml1[j]); C1 = ex2(m1 - M) * C1 + ex2(ml1[j] - M) * v1[j]; m1 = bl1[j] + M; } }
.LBB0_271:
	s_or_b64 exec, exec, s[8:9]
	v_max_f32_e32 v62, v59, v61
	v_sub_f32_e32 v60, v61, v62
	v_sub_f32_e32 v59, v59, v62
	v_exp_f32_e32 v63, v60
	v_exp_f32_e32 v64, v59
	s_mov_b64 s[4:5], 0x135c0c00
	v_lshl_add_u64 v[60:61], v[102:103], 0, s[4:5]
	s_waitcnt vmcnt(16)
	v_mul_f32_e32 v59, v110, v63
	v_fmac_f32_e32 v59, v58, v64
	v_add_f32_e32 v58, v65, v62
	global_store_dword v[60:61], v59, off
	s_and_saveexec_b64 s[8:9], s[42:43]
	s_cbranch_execz .LBB0_273
	v_add_co_u32_e32 v60, vcc, 0x175e4000, v100
	s_nop 1
	v_addc_co_u32_e32 v61, vcc, 0, v101, vcc
	global_store_dword v[60:61], v58, off offset:48

; __device__ __forceinline__ float ex2(float x) { return __builtin_amdgcn_exp2f(x); }
; __device__ __forceinline__ void ml_scan_phase(float* KV, const float* MLOC, const float* BLAST, float* MPREV) {
;     ...
;         for (int j = 0; j < 16; ++j) { p0[(size_t)(k0 + j) * ML_KVSZ] = C0; if (el0 == 0) MPREV[bh0 * 128 + k0 + j] = m0;
;             const float M = fmaxf(m0, ml0[j]); C0 = ex2(m0 - M) * C0 + ex2(ml0[j] - M) * v0[j]; m0 = bl0[j] + M; }
;         if (e1 >= 0) {
; #pragma unroll
;             for (int j = 0; j < 16; ++j) { p1[(size_t)(k0 + j) * ML_KVSZ] = C1; if (el1 == 0) MPREV[bh1 * 128 + k0 + j] = m1;
;                 const float M = fmaxf(m1, ml1[j]); C1 = ex2(m1 - M) * C1 + ex2(ml1[j] - M) * v1[j]; m1 = bl1[j] + M; } }
.LBB0_282:
	s_or_b64 exec, exec, s[10:11]
	v_max_f32_e32 v54, v99, v18
	v_sub_f32_e32 v55, v18, v54
	v_sub_f32_e32 v52, v99, v54
	v_exp_f32_e32 v55, v55
	v_exp_f32_e32 v56, v52
	v_add_co_u32_e32 v58, vcc, 0x13568000, v96
	v_mul_f32_e32 v52, v55, v2
	v_fmac_f32_e32 v52, v98, v56
	v_add_f32_e32 v54, v54, v38
	v_addc_co_u32_e32 v59, vcc, 0, v97, vcc
	global_store_dword v[58:59], v52, off offset:256
	s_and_saveexec_b64 s[10:11], s[44:45]
	s_cbranch_execz .LBB0_284
	v_add_co_u32_e32 v58, vcc, 0x175e4000, v94
	s_nop 1
	v_addc_co_u32_e32 v59, vcc, 0, v95, vcc
	global_store_dword v[58:59], v54, off offset:4
.LBB0_284:
	s_or_b64 exec, exec, s[10:11]
	v_max_f32_e32 v55, v54, v19
	v_sub_f32_e32 v56, v19, v55
	v_sub_f32_e32 v54, v54, v55
	v_exp_f32_e32 v56, v56
	v_exp_f32_e32 v58, v54
	v_mul_f32_e32 v54, v3, v56
	v_fmac_f32_e32 v54, v52, v58
	v_add_co_u32_e32 v58, vcc, 0x13570000, v96
	v_add_f32_e32 v52, v39, v55
	s_nop 0
	v_addc_co_u32_e32 v59, vcc, 0, v97, vcc
	global_store_dword v[58:59], v54, off offset:512
	s_and_saveexec_b64 s[10:11], s[44:45]
	s_cbranch_execz .LBB0_286
	v_add_co_u32_e32 v58, vcc, 0x175e4000, v94
	s_nop 1
	v_addc_co_u32_e32 v59, vcc, 0, v95, vcc
	global_store_dword v[58:59], v52, off offset:8
.LBB0_286:
	s_or_b64 exec, exec, s[10:11]
	v_max_f32_e32 v55, v52, v20
	v_sub_f32_e32 v56, v20, v55
	v_sub_f32_e32 v52, v52, v55
	v_exp_f32_e32 v56, v56
	v_exp_f32_e32 v58, v52
	v_mul_f32_e32 v52, v4, v56
	v_fmac_f32_e32 v52, v54, v58
	v_add_co_u32_e32 v58, vcc, 0x13578000, v96
	v_add_f32_e32 v54, v40, v55
	s_nop 0
	v_addc_co_u32_e32 v59, vcc, 0, v97, vcc
	global_store_dword v[58:59], v52, off offset:768
	s_and_saveexec_b64 s[10:11], s[44:45]
	s_cbranch_execz .LBB0_288
	v_add_co_u32_e32 v58, vcc, 0x175e4000, v94
	s_nop 1
	v_addc_co_u32_e32 v59, vcc, 0, v95, vcc
	global_store_dword v[58:59], v54, off offset:12
.LBB0_288:
	s_or_b64 exec, exec, s[10:11]
	v_max_f32_e32 v55, v54, v21
	v_sub_f32_e32 v56, v21, v55
	v_sub_f32_e32 v54, v54, v55
	v_exp_f32_e32 v56, v56
	v_exp_f32_e32 v58, v54
	v_mul_f32_e32 v54, v5, v56
	v_fmac_f32_e32 v54, v52, v58
	v_add_co_u32_e32 v58, vcc, 0x13580000, v96
	v_add_f32_e32 v52, v41, v55
	s_nop 0
	v_addc_co_u32_e32 v59, vcc, 0, v97, vcc
	global_store_dword v[58:59], v54, off offset:1024
	s_and_saveexec_b64 s[10:11], s[44:45]
	s_cbranch_execz .LBB0_290
	v_add_co_u32_e32 v58, vcc, 0x175e4000, v94
	s_nop 1
	v_addc_co_u32_e32 v59, vcc, 0, v95, vcc
	global_store_dword v[58:59], v52, off offset:16
.LBB0_290:
	s_or_b64 exec, exec, s[10:11]
	v_max_f32_e32 v55, v52, v30
	v_sub_f32_e32 v56, v30, v55
	v_sub_f32_e32 v52, v52, v55
	v_exp_f32_e32 v56, v56
	v_exp_f32_e32 v58, v52
	v_mul_f32_e32 v52, v6, v56
	v_fmac_f32_e32 v52, v54, v58
	v_add_co_u32_e32 v58, vcc, 0x13588000, v96
	v_add_f32_e32 v54, v46, v55
	s_nop 0
	v_addc_co_u32_e32 v59, vcc, 0, v97, vcc
	global_store_dword v[58:59], v52, off offset:1280
	s_and_saveexec_b64 s[10:11], s[44:45]
	s_cbranch_execz .LBB0_292
	v_add_co_u32_e32 v58, vcc, 0x175e4000, v94
	s_nop 1
	v_addc_co_u32_e32 v59, vcc, 0, v95, vcc
	global_store_dword v[58:59], v54, off offset:20
.LBB0_292:
	s_or_b64 exec, exec, s[10:11]
	v_max_f32_e32 v55, v54, v31
	v_sub_f32_e32 v56, v31, v55
	v_sub_f32_e32 v54, v54, v55
	v_exp_f32_e32 v56, v56
	v_exp_f32_e32 v58, v54
	v_mul_f32_e32 v54, v7, v56
	v_fmac_f32_e32 v54, v52, v58
	v_add_co_u32_e32 v58, vcc, 0x13590000, v96
	v_add_f32_e32 v52, v47, v55
	s_nop 0
	v_addc_co_u32_e32 v59, vcc, 0, v97, vcc
	global_store_dword v[58:59], v54, off offset:1536
	s_and_saveexec_b64 s[10:11], s[44:45]
	s_cbranch_execz .LBB0_294
	v_add_co_u32_e32 v58, vcc, 0x175e4000, v94
	s_nop 1
	v_addc_co_u32_e32 v59, vcc, 0, v95, vcc
	global_store_dword v[58:59], v52, off offset:24
.LBB0_294:
	s_or_b64 exec, exec, s[10:11]
	v_max_f32_e32 v55, v52, v32
	v_sub_f32_e32 v56, v32, v55
	v_sub_f32_e32 v52, v52, v55
	v_exp_f32_e32 v56, v56
	v_exp_f32_e32 v58, v52
	v_mul_f32_e32 v52, v8, v56
	v_fmac_f32_e32 v52, v54, v58
	v_add_co_u32_e32 v58, vcc, 0x13598000, v96
	v_add_f32_e32 v54, v48, v55
	s_nop 0
	v_addc_co_u32_e32 v59, vcc, 0, v97, vcc
	global_store_dword v[58:59], v52, off offset:1792
	s_and_saveexec_b64 s[10:11], s[44:45]
	s_cbranch_execz .LBB0_296
	v_add_co_u32_e32 v58, vcc, 0x175e4000, v94
	s_nop 1
	v_addc_co_u32_e32 v59, vcc, 0, v95, vcc
	global_store_dword v[58:59], v54, off offset:28
.LBB0_296:
	s_or_b64 exec, exec, s[10:11]
	v_max_f32_e32 v55, v54, v33
	v_sub_f32_e32 v56, v33, v55
	v_sub_f32_e32 v54, v54, v55
	v_exp_f32_e32 v56, v56
	v_exp_f32_e32 v58, v54
	v_mul_f32_e32 v54, v9, v56
	v_fmac_f32_e32 v54, v52, v58
	v_add_co_u32_e32 v58, vcc, 0x135a0000, v96
	v_add_f32_e32 v52, v49, v55
	s_nop 0
	v_addc_co_u32_e32 v59, vcc, 0, v97, vcc
	global_store_dword v[58:59], v54, off offset:2048
	s_and_saveexec_b64 s[10:11], s[44:45]
	s_cbranch_execz .LBB0_298
	v_add_co_u32_e32 v58, vcc, 0x175e4000, v94
	s_nop 1
	v_addc_co_u32_e32 v59, vcc, 0, v95, vcc
	global_store_dword v[58:59], v52, off offset:32
; __device__ __forceinline__ float ex2(float x) { return __builtin_amdgcn_exp2f(x); }
; __device__ __forceinline__ void ml_scan_phase(float* KV, const float* MLOC, const float* BLAST, float* MPREV) {
;     ...
;         for (int j = 0; j < 16; ++j) { p0[(size_t)(k0 + j) * ML_KVSZ] = C0; if (el0 == 0) MPREV[bh0 * 128 + k0 + j] = m0;
;             const float M = fmaxf(m0, ml0[j]); C0 = ex2(m0 - M) * C0 + ex2(ml0[j] - M) * v0[j]; m0 = bl0[j] + M; }
;         if (e1 >= 0) {
; #pragma unroll
;             for (int j = 0; j < 16; ++j) { p1[(size_t)(k0 + j) * ML_KVSZ] = C1; if (el1 == 0) MPREV[bh1 * 128 + k0 + j] = m1;
;                 const float M = fmaxf(m1, ml1[j]); C1 = ex2(m1 - M) * C1 + ex2(ml1[j] - M) * v1[j]; m1 = bl1[j] + M; } }
.LBB0_298:
	s_or_b64 exec, exec, s[10:11]
	v_max_f32_e32 v55, v52, v26
	v_sub_f32_e32 v56, v26, v55
	v_sub_f32_e32 v52, v52, v55
	v_exp_f32_e32 v56, v56
	v_exp_f32_e32 v58, v52
	v_mul_f32_e32 v52, v10, v56
	v_fmac_f32_e32 v52, v54, v58
	v_add_co_u32_e32 v58, vcc, 0x135a8000, v96
	v_add_f32_e32 v54, v42, v55
	s_nop 0
	v_addc_co_u32_e32 v59, vcc, 0, v97, vcc
	global_store_dword v[58:59], v52, off offset:2304
	s_and_saveexec_b64 s[10:11], s[44:45]
	s_cbranch_execz .LBB0_300
	v_add_co_u32_e32 v58, vcc, 0x175e4000, v94
	s_nop 1
	v_addc_co_u32_e32 v59, vcc, 0, v95, vcc
	global_store_dword v[58:59], v54, off offset:36
.LBB0_300:
	s_or_b64 exec, exec, s[10:11]
	v_max_f32_e32 v55, v54, v27
	v_sub_f32_e32 v56, v27, v55
	v_sub_f32_e32 v54, v54, v55
	v_exp_f32_e32 v56, v56
	v_exp_f32_e32 v58, v54
	v_mul_f32_e32 v54, v11, v56
	v_fmac_f32_e32 v54, v52, v58
	v_add_co_u32_e32 v58, vcc, 0x135b0000, v96
	v_add_f32_e32 v52, v43, v55
	s_nop 0
	v_addc_co_u32_e32 v59, vcc, 0, v97, vcc
	global_store_dword v[58:59], v54, off offset:2560
	s_and_saveexec_b64 s[10:11], s[44:45]
	s_cbranch_execz .LBB0_302
	v_add_co_u32_e32 v58, vcc, 0x175e4000, v94
	s_nop 1
	v_addc_co_u32_e32 v59, vcc, 0, v95, vcc
	global_store_dword v[58:59], v52, off offset:40
.LBB0_302:
	s_or_b64 exec, exec, s[10:11]
	v_max_f32_e32 v55, v52, v28
	v_sub_f32_e32 v56, v28, v55
	v_sub_f32_e32 v52, v52, v55
	v_exp_f32_e32 v56, v56
	v_exp_f32_e32 v58, v52
	v_mul_f32_e32 v52, v12, v56
	v_fmac_f32_e32 v52, v54, v58
	v_add_co_u32_e32 v58, vcc, 0x135b8000, v96
	v_add_f32_e32 v54, v44, v55
	s_nop 0
	v_addc_co_u32_e32 v59, vcc, 0, v97, vcc
	global_store_dword v[58:59], v52, off offset:2816
	s_and_saveexec_b64 s[10:11], s[44:45]
	s_cbranch_execz .LBB0_304
	v_add_co_u32_e32 v58, vcc, 0x175e4000, v94
	s_nop 1
	v_addc_co_u32_e32 v59, vcc, 0, v95, vcc
	global_store_dword v[58:59], v54, off offset:44
.LBB0_304:
	s_or_b64 exec, exec, s[10:11]
	v_max_f32_e32 v55, v54, v29
	v_sub_f32_e32 v56, v29, v55
	v_sub_f32_e32 v54, v54, v55
	v_exp_f32_e32 v56, v56
	v_exp_f32_e32 v58, v54
	v_mul_f32_e32 v54, v13, v56
	v_fmac_f32_e32 v54, v52, v58
	v_add_co_u32_e32 v58, vcc, 0x135c0000, v96
	v_add_f32_e32 v52, v45, v55
	s_nop 0
	v_addc_co_u32_e32 v59, vcc, 0, v97, vcc
	global_store_dword v[58:59], v54, off offset:3072
	s_and_saveexec_b64 s[10:11], s[44:45]
	s_cbranch_execz .LBB0_306
	v_add_co_u32_e32 v58, vcc, 0x175e4000, v94
	s_nop 1
	v_addc_co_u32_e32 v59, vcc, 0, v95, vcc
	global_store_dword v[58:59], v52, off offset:48
.LBB0_306:
	s_or_b64 exec, exec, s[10:11]
	v_max_f32_e32 v55, v52, v22
	v_sub_f32_e32 v56, v22, v55
	v_sub_f32_e32 v52, v52, v55
	v_exp_f32_e32 v56, v56
	v_exp_f32_e32 v58, v52
	v_mul_f32_e32 v52, v14, v56
	v_fmac_f32_e32 v52, v54, v58
	v_add_co_u32_e32 v58, vcc, 0x135c8000, v96
	v_add_f32_e32 v54, v34, v55
	s_nop 0
	v_addc_co_u32_e32 v59, vcc, 0, v97, vcc
	global_store_dword v[58:59], v52, off offset:3328
	s_and_saveexec_b64 s[10:11], s[44:45]
	s_cbranch_execz .LBB0_308
	v_add_co_u32_e32 v58, vcc, 0x175e4000, v94
	s_nop 1
	v_addc_co_u32_e32 v59, vcc, 0, v95, vcc
	global_store_dword v[58:59], v54, off offset:52
.LBB0_308:
	s_or_b64 exec, exec, s[10:11]
	v_max_f32_e32 v55, v54, v23
	v_sub_f32_e32 v56, v23, v55
	v_sub_f32_e32 v54, v54, v55
	v_exp_f32_e32 v56, v56
	v_exp_f32_e32 v58, v54
	v_mul_f32_e32 v54, v15, v56
	v_fmac_f32_e32 v54, v52, v58
	v_add_co_u32_e32 v58, vcc, 0x135d0000, v96
	v_add_f32_e32 v52, v35, v55
	s_nop 0
	v_addc_co_u32_e32 v59, vcc, 0, v97, vcc
	global_store_dword v[58:59], v54, off offset:3584
	s_and_saveexec_b64 s[10:11], s[44:45]
	s_cbranch_execz .LBB0_310
	v_add_co_u32_e32 v58, vcc, 0x175e4000, v94
	s_nop 1
	v_addc_co_u32_e32 v59, vcc, 0, v95, vcc
	global_store_dword v[58:59], v52, off offset:56
.LBB0_310:
	s_or_b64 exec, exec, s[10:11]
	v_max_f32_e32 v55, v52, v24
	v_sub_f32_e32 v56, v24, v55
	v_sub_f32_e32 v52, v52, v55
	v_exp_f32_e32 v56, v56
	v_exp_f32_e32 v58, v52
	v_mul_f32_e32 v52, v16, v56
	v_fmac_f32_e32 v52, v54, v58
	v_add_co_u32_e32 v58, vcc, 0x135d8000, v96
	v_add_f32_e32 v54, v36, v55
	s_nop 0
	v_addc_co_u32_e32 v59, vcc, 0, v97, vcc
	global_store_dword v[58:59], v52, off offset:3840
	s_and_saveexec_b64 s[10:11], s[44:45]
	s_cbranch_execz .LBB0_243
	v_add_co_u32_e32 v58, vcc, 0x175e4000, v94
	s_nop 1
	v_addc_co_u32_e32 v59, vcc, 0, v95, vcc
	global_store_dword v[58:59], v54, off offset:60
	s_branch .LBB0_243
